# P12 carry-in loop rewritten: 32 chunks of (decay,state) loads in flight per batch instead of 8+1
# speedup vs baseline: 1.0078x; 1.0078x over previous
.LBB0_1557:
	v_ashrrev_i32_e32 v6, 9, v12
	v_and_b32_e32 v3, 0x7f, v6
	v_bfe_u32 v14, v13, 1, 9
	v_ashrrev_i32_e32 v7, 31, v6
	v_cmp_ne_u32_e32 vcc, 0, v3
	v_mov_b32_e32 v5, 0
	v_mov_b32_e32 v4, 0
	s_and_saveexec_b64 s[38:39], vcc
	s_cbranch_execz .LBB0_1567
	v_readfirstlane_b32 s0, v3
	v_and_b32_e32 v8, 0xffffff80, v6
	v_lshlrev_b32_e32 v8, 12, v8
	v_lshl_or_b32 v8, v14, 3, v8
	v_mov_b32_e32 v9, 0
	v_lshl_add_u64 v[10:11], s[16:17], 0, v[8:9]
	v_lshl_add_u64 v[150:151], s[14:15], 0, v[8:9]
	v_mov_b32_e32 v4, 0
	v_mov_b32_e32 v5, 0
.Lc12_batch:
	global_load_dwordx2 v[16:17], v[10:11], off
	global_load_dwordx2 v[80:81], v[150:151], off
	v_lshl_add_u64 v[10:11], v[10:11], 0, s[36:37]
	v_lshl_add_u64 v[150:151], v[150:151], 0, s[36:37]
	s_cmp_le_u32 s0, 1
	s_cbranch_scc1 .Lc12_ld_done
	global_load_dwordx2 v[18:19], v[10:11], off
	global_load_dwordx2 v[82:83], v[150:151], off
	v_lshl_add_u64 v[10:11], v[10:11], 0, s[36:37]
	v_lshl_add_u64 v[150:151], v[150:151], 0, s[36:37]
	s_cmp_le_u32 s0, 2
	s_cbranch_scc1 .Lc12_ld_done
	global_load_dwordx2 v[20:21], v[10:11], off
	global_load_dwordx2 v[84:85], v[150:151], off
	v_lshl_add_u64 v[10:11], v[10:11], 0, s[36:37]
	v_lshl_add_u64 v[150:151], v[150:151], 0, s[36:37]
	s_cmp_le_u32 s0, 3
	s_cbranch_scc1 .Lc12_ld_done
	global_load_dwordx2 v[22:23], v[10:11], off
	global_load_dwordx2 v[86:87], v[150:151], off
	v_lshl_add_u64 v[10:11], v[10:11], 0, s[36:37]
	v_lshl_add_u64 v[150:151], v[150:151], 0, s[36:37]
	s_cmp_le_u32 s0, 4
	s_cbranch_scc1 .Lc12_ld_done
	global_load_dwordx2 v[24:25], v[10:11], off
	global_load_dwordx2 v[88:89], v[150:151], off
	v_lshl_add_u64 v[10:11], v[10:11], 0, s[36:37]
	v_lshl_add_u64 v[150:151], v[150:151], 0, s[36:37]
	s_cmp_le_u32 s0, 5
	s_cbranch_scc1 .Lc12_ld_done
	global_load_dwordx2 v[26:27], v[10:11], off
	global_load_dwordx2 v[90:91], v[150:151], off
	v_lshl_add_u64 v[10:11], v[10:11], 0, s[36:37]
	v_lshl_add_u64 v[150:151], v[150:151], 0, s[36:37]
	s_cmp_le_u32 s0, 6
	s_cbranch_scc1 .Lc12_ld_done
	global_load_dwordx2 v[28:29], v[10:11], off
	global_load_dwordx2 v[92:93], v[150:151], off
	v_lshl_add_u64 v[10:11], v[10:11], 0, s[36:37]
	v_lshl_add_u64 v[150:151], v[150:151], 0, s[36:37]
	s_cmp_le_u32 s0, 7
	s_cbranch_scc1 .Lc12_ld_done
	global_load_dwordx2 v[30:31], v[10:11], off
	global_load_dwordx2 v[94:95], v[150:151], off
	v_lshl_add_u64 v[10:11], v[10:11], 0, s[36:37]
	v_lshl_add_u64 v[150:151], v[150:151], 0, s[36:37]
	s_cmp_le_u32 s0, 8
	s_cbranch_scc1 .Lc12_ld_done
	global_load_dwordx2 v[32:33], v[10:11], off
	global_load_dwordx2 v[96:97], v[150:151], off
	v_lshl_add_u64 v[10:11], v[10:11], 0, s[36:37]
	v_lshl_add_u64 v[150:151], v[150:151], 0, s[36:37]
	s_cmp_le_u32 s0, 9
	s_cbranch_scc1 .Lc12_ld_done
	global_load_dwordx2 v[34:35], v[10:11], off
	global_load_dwordx2 v[98:99], v[150:151], off
	v_lshl_add_u64 v[10:11], v[10:11], 0, s[36:37]
	v_lshl_add_u64 v[150:151], v[150:151], 0, s[36:37]
	s_cmp_le_u32 s0, 10
	s_cbranch_scc1 .Lc12_ld_done
	global_load_dwordx2 v[36:37], v[10:11], off
	global_load_dwordx2 v[100:101], v[150:151], off
	v_lshl_add_u64 v[10:11], v[10:11], 0, s[36:37]
	v_lshl_add_u64 v[150:151], v[150:151], 0, s[36:37]
	s_cmp_le_u32 s0, 11
	s_cbranch_scc1 .Lc12_ld_done
	global_load_dwordx2 v[38:39], v[10:11], off
	global_load_dwordx2 v[102:103], v[150:151], off
	v_lshl_add_u64 v[10:11], v[10:11], 0, s[36:37]
	v_lshl_add_u64 v[150:151], v[150:151], 0, s[36:37]
	s_cmp_le_u32 s0, 12
	s_cbranch_scc1 .Lc12_ld_done
	global_load_dwordx2 v[40:41], v[10:11], off
	global_load_dwordx2 v[104:105], v[150:151], off
	v_lshl_add_u64 v[10:11], v[10:11], 0, s[36:37]
	v_lshl_add_u64 v[150:151], v[150:151], 0, s[36:37]
	s_cmp_le_u32 s0, 13
	s_cbranch_scc1 .Lc12_ld_done
	global_load_dwordx2 v[42:43], v[10:11], off
	global_load_dwordx2 v[106:107], v[150:151], off
	v_lshl_add_u64 v[10:11], v[10:11], 0, s[36:37]
	v_lshl_add_u64 v[150:151], v[150:151], 0, s[36:37]
	s_cmp_le_u32 s0, 14
	s_cbranch_scc1 .Lc12_ld_done
	global_load_dwordx2 v[44:45], v[10:11], off
	global_load_dwordx2 v[108:109], v[150:151], off
	v_lshl_add_u64 v[10:11], v[10:11], 0, s[36:37]
	v_lshl_add_u64 v[150:151], v[150:151], 0, s[36:37]
	s_cmp_le_u32 s0, 15
	s_cbranch_scc1 .Lc12_ld_done
	global_load_dwordx2 v[46:47], v[10:11], off
	global_load_dwordx2 v[110:111], v[150:151], off
	v_lshl_add_u64 v[10:11], v[10:11], 0, s[36:37]
	v_lshl_add_u64 v[150:151], v[150:151], 0, s[36:37]
	s_cmp_le_u32 s0, 16
	s_cbranch_scc1 .Lc12_ld_done
	global_load_dwordx2 v[48:49], v[10:11], off
	global_load_dwordx2 v[112:113], v[150:151], off
	v_lshl_add_u64 v[10:11], v[10:11], 0, s[36:37]
	v_lshl_add_u64 v[150:151], v[150:151], 0, s[36:37]
	s_cmp_le_u32 s0, 17
	s_cbranch_scc1 .Lc12_ld_done
	global_load_dwordx2 v[50:51], v[10:11], off
	global_load_dwordx2 v[114:115], v[150:151], off
	v_lshl_add_u64 v[10:11], v[10:11], 0, s[36:37]
	v_lshl_add_u64 v[150:151], v[150:151], 0, s[36:37]
	s_cmp_le_u32 s0, 18
	s_cbranch_scc1 .Lc12_ld_done
	global_load_dwordx2 v[52:53], v[10:11], off
	global_load_dwordx2 v[116:117], v[150:151], off
	v_lshl_add_u64 v[10:11], v[10:11], 0, s[36:37]
	v_lshl_add_u64 v[150:151], v[150:151], 0, s[36:37]
	s_cmp_le_u32 s0, 19
	s_cbranch_scc1 .Lc12_ld_done
	global_load_dwordx2 v[54:55], v[10:11], off
	global_load_dwordx2 v[118:119], v[150:151], off
	v_lshl_add_u64 v[10:11], v[10:11], 0, s[36:37]
	v_lshl_add_u64 v[150:151], v[150:151], 0, s[36:37]
	s_cmp_le_u32 s0, 20
	s_cbranch_scc1 .Lc12_ld_done
	global_load_dwordx2 v[56:57], v[10:11], off
	global_load_dwordx2 v[120:121], v[150:151], off
	v_lshl_add_u64 v[10:11], v[10:11], 0, s[36:37]
	v_lshl_add_u64 v[150:151], v[150:151], 0, s[36:37]
	s_cmp_le_u32 s0, 21
	s_cbranch_scc1 .Lc12_ld_done
	global_load_dwordx2 v[58:59], v[10:11], off
	global_load_dwordx2 v[122:123], v[150:151], off
	v_lshl_add_u64 v[10:11], v[10:11], 0, s[36:37]
	v_lshl_add_u64 v[150:151], v[150:151], 0, s[36:37]
	s_cmp_le_u32 s0, 22
	s_cbranch_scc1 .Lc12_ld_done
	global_load_dwordx2 v[60:61], v[10:11], off
	global_load_dwordx2 v[124:125], v[150:151], off
	v_lshl_add_u64 v[10:11], v[10:11], 0, s[36:37]
	v_lshl_add_u64 v[150:151], v[150:151], 0, s[36:37]
	s_cmp_le_u32 s0, 23
	s_cbranch_scc1 .Lc12_ld_done
	global_load_dwordx2 v[62:63], v[10:11], off
	global_load_dwordx2 v[126:127], v[150:151], off
	v_lshl_add_u64 v[10:11], v[10:11], 0, s[36:37]
	v_lshl_add_u64 v[150:151], v[150:151], 0, s[36:37]
	s_cmp_le_u32 s0, 24
	s_cbranch_scc1 .Lc12_ld_done
	global_load_dwordx2 v[64:65], v[10:11], off
	global_load_dwordx2 v[128:129], v[150:151], off
	v_lshl_add_u64 v[10:11], v[10:11], 0, s[36:37]
	v_lshl_add_u64 v[150:151], v[150:151], 0, s[36:37]
	s_cmp_le_u32 s0, 25
	s_cbranch_scc1 .Lc12_ld_done
	global_load_dwordx2 v[66:67], v[10:11], off
	global_load_dwordx2 v[130:131], v[150:151], off
	v_lshl_add_u64 v[10:11], v[10:11], 0, s[36:37]
	v_lshl_add_u64 v[150:151], v[150:151], 0, s[36:37]
	s_cmp_le_u32 s0, 26
	s_cbranch_scc1 .Lc12_ld_done
	global_load_dwordx2 v[68:69], v[10:11], off
	global_load_dwordx2 v[132:133], v[150:151], off
	v_lshl_add_u64 v[10:11], v[10:11], 0, s[36:37]
	v_lshl_add_u64 v[150:151], v[150:151], 0, s[36:37]
	s_cmp_le_u32 s0, 27
	s_cbranch_scc1 .Lc12_ld_done
	global_load_dwordx2 v[70:71], v[10:11], off
	global_load_dwordx2 v[134:135], v[150:151], off
	v_lshl_add_u64 v[10:11], v[10:11], 0, s[36:37]
	v_lshl_add_u64 v[150:151], v[150:151], 0, s[36:37]
	s_cmp_le_u32 s0, 28
	s_cbranch_scc1 .Lc12_ld_done
	global_load_dwordx2 v[72:73], v[10:11], off
	global_load_dwordx2 v[136:137], v[150:151], off
	v_lshl_add_u64 v[10:11], v[10:11], 0, s[36:37]
	v_lshl_add_u64 v[150:151], v[150:151], 0, s[36:37]
	s_cmp_le_u32 s0, 29
	s_cbranch_scc1 .Lc12_ld_done
	global_load_dwordx2 v[74:75], v[10:11], off
	global_load_dwordx2 v[138:139], v[150:151], off
	v_lshl_add_u64 v[10:11], v[10:11], 0, s[36:37]
	v_lshl_add_u64 v[150:151], v[150:151], 0, s[36:37]
	s_cmp_le_u32 s0, 30
	s_cbranch_scc1 .Lc12_ld_done
	global_load_dwordx2 v[76:77], v[10:11], off
	global_load_dwordx2 v[140:141], v[150:151], off
	v_lshl_add_u64 v[10:11], v[10:11], 0, s[36:37]
	v_lshl_add_u64 v[150:151], v[150:151], 0, s[36:37]
	s_cmp_le_u32 s0, 31
	s_cbranch_scc1 .Lc12_ld_done
	global_load_dwordx2 v[78:79], v[10:11], off
	global_load_dwordx2 v[142:143], v[150:151], off
	v_lshl_add_u64 v[10:11], v[10:11], 0, s[36:37]
	v_lshl_add_u64 v[150:151], v[150:151], 0, s[36:37]
.Lc12_ld_done:
	s_waitcnt vmcnt(0)
	v_mul_f32_e32 v80, 0x3fb8aa3b, v80
	v_mul_f32_e32 v81, 0x3fb8aa3b, v81
	v_exp_f32_e32 v80, v80
	v_exp_f32_e32 v81, v81
	s_nop 0
	v_pk_fma_f32 v[4:5], v[4:5], v[80:81], v[16:17]
	s_cmp_le_u32 s0, 1
	s_cbranch_scc1 .Lc12_cmp_done
	v_mul_f32_e32 v82, 0x3fb8aa3b, v82
	v_mul_f32_e32 v83, 0x3fb8aa3b, v83
	v_exp_f32_e32 v82, v82
	v_exp_f32_e32 v83, v83
	s_nop 0
	v_pk_fma_f32 v[4:5], v[4:5], v[82:83], v[18:19]
	s_cmp_le_u32 s0, 2
	s_cbranch_scc1 .Lc12_cmp_done
	v_mul_f32_e32 v84, 0x3fb8aa3b, v84
	v_mul_f32_e32 v85, 0x3fb8aa3b, v85
	v_exp_f32_e32 v84, v84
	v_exp_f32_e32 v85, v85
	s_nop 0
	v_pk_fma_f32 v[4:5], v[4:5], v[84:85], v[20:21]
	s_cmp_le_u32 s0, 3
	s_cbranch_scc1 .Lc12_cmp_done
	v_mul_f32_e32 v86, 0x3fb8aa3b, v86
	v_mul_f32_e32 v87, 0x3fb8aa3b, v87
	v_exp_f32_e32 v86, v86
	v_exp_f32_e32 v87, v87
	s_nop 0
	v_pk_fma_f32 v[4:5], v[4:5], v[86:87], v[22:23]
	s_cmp_le_u32 s0, 4
	s_cbranch_scc1 .Lc12_cmp_done
	v_mul_f32_e32 v88, 0x3fb8aa3b, v88
	v_mul_f32_e32 v89, 0x3fb8aa3b, v89
	v_exp_f32_e32 v88, v88
	v_exp_f32_e32 v89, v89
	s_nop 0
	v_pk_fma_f32 v[4:5], v[4:5], v[88:89], v[24:25]
	s_cmp_le_u32 s0, 5
	s_cbranch_scc1 .Lc12_cmp_done
	v_mul_f32_e32 v90, 0x3fb8aa3b, v90
	v_mul_f32_e32 v91, 0x3fb8aa3b, v91
	v_exp_f32_e32 v90, v90
	v_exp_f32_e32 v91, v91
	s_nop 0
	v_pk_fma_f32 v[4:5], v[4:5], v[90:91], v[26:27]
	s_cmp_le_u32 s0, 6
	s_cbranch_scc1 .Lc12_cmp_done
	v_mul_f32_e32 v92, 0x3fb8aa3b, v92
	v_mul_f32_e32 v93, 0x3fb8aa3b, v93
	v_exp_f32_e32 v92, v92
	v_exp_f32_e32 v93, v93
	s_nop 0
	v_pk_fma_f32 v[4:5], v[4:5], v[92:93], v[28:29]
	s_cmp_le_u32 s0, 7
	s_cbranch_scc1 .Lc12_cmp_done
	v_mul_f32_e32 v94, 0x3fb8aa3b, v94
	v_mul_f32_e32 v95, 0x3fb8aa3b, v95
	v_exp_f32_e32 v94, v94
	v_exp_f32_e32 v95, v95
	s_nop 0
	v_pk_fma_f32 v[4:5], v[4:5], v[94:95], v[30:31]
	s_cmp_le_u32 s0, 8
	s_cbranch_scc1 .Lc12_cmp_done
	v_mul_f32_e32 v96, 0x3fb8aa3b, v96
	v_mul_f32_e32 v97, 0x3fb8aa3b, v97
	v_exp_f32_e32 v96, v96
	v_exp_f32_e32 v97, v97
	s_nop 0
	v_pk_fma_f32 v[4:5], v[4:5], v[96:97], v[32:33]
	s_cmp_le_u32 s0, 9
	s_cbranch_scc1 .Lc12_cmp_done
	v_mul_f32_e32 v98, 0x3fb8aa3b, v98
	v_mul_f32_e32 v99, 0x3fb8aa3b, v99
	v_exp_f32_e32 v98, v98
	v_exp_f32_e32 v99, v99
	s_nop 0
	v_pk_fma_f32 v[4:5], v[4:5], v[98:99], v[34:35]
	s_cmp_le_u32 s0, 10
	s_cbranch_scc1 .Lc12_cmp_done
	v_mul_f32_e32 v100, 0x3fb8aa3b, v100
	v_mul_f32_e32 v101, 0x3fb8aa3b, v101
	v_exp_f32_e32 v100, v100
	v_exp_f32_e32 v101, v101
	s_nop 0
	v_pk_fma_f32 v[4:5], v[4:5], v[100:101], v[36:37]
	s_cmp_le_u32 s0, 11
	s_cbranch_scc1 .Lc12_cmp_done
	v_mul_f32_e32 v102, 0x3fb8aa3b, v102
	v_mul_f32_e32 v103, 0x3fb8aa3b, v103
	v_exp_f32_e32 v102, v102
	v_exp_f32_e32 v103, v103
	s_nop 0
	v_pk_fma_f32 v[4:5], v[4:5], v[102:103], v[38:39]
	s_cmp_le_u32 s0, 12
	s_cbranch_scc1 .Lc12_cmp_done
	v_mul_f32_e32 v104, 0x3fb8aa3b, v104
	v_mul_f32_e32 v105, 0x3fb8aa3b, v105
	v_exp_f32_e32 v104, v104
	v_exp_f32_e32 v105, v105
	s_nop 0
	v_pk_fma_f32 v[4:5], v[4:5], v[104:105], v[40:41]
	s_cmp_le_u32 s0, 13
	s_cbranch_scc1 .Lc12_cmp_done
	v_mul_f32_e32 v106, 0x3fb8aa3b, v106
	v_mul_f32_e32 v107, 0x3fb8aa3b, v107
	v_exp_f32_e32 v106, v106
	v_exp_f32_e32 v107, v107
	s_nop 0
	v_pk_fma_f32 v[4:5], v[4:5], v[106:107], v[42:43]
	s_cmp_le_u32 s0, 14
	s_cbranch_scc1 .Lc12_cmp_done
	v_mul_f32_e32 v108, 0x3fb8aa3b, v108
	v_mul_f32_e32 v109, 0x3fb8aa3b, v109
	v_exp_f32_e32 v108, v108
	v_exp_f32_e32 v109, v109
	s_nop 0
	v_pk_fma_f32 v[4:5], v[4:5], v[108:109], v[44:45]
	s_cmp_le_u32 s0, 15
	s_cbranch_scc1 .Lc12_cmp_done
	v_mul_f32_e32 v110, 0x3fb8aa3b, v110
	v_mul_f32_e32 v111, 0x3fb8aa3b, v111
	v_exp_f32_e32 v110, v110
	v_exp_f32_e32 v111, v111
	s_nop 0
	v_pk_fma_f32 v[4:5], v[4:5], v[110:111], v[46:47]
	s_cmp_le_u32 s0, 16
	s_cbranch_scc1 .Lc12_cmp_done
	v_mul_f32_e32 v112, 0x3fb8aa3b, v112
	v_mul_f32_e32 v113, 0x3fb8aa3b, v113
	v_exp_f32_e32 v112, v112
	v_exp_f32_e32 v113, v113
	s_nop 0
	v_pk_fma_f32 v[4:5], v[4:5], v[112:113], v[48:49]
	s_cmp_le_u32 s0, 17
	s_cbranch_scc1 .Lc12_cmp_done
	v_mul_f32_e32 v114, 0x3fb8aa3b, v114
	v_mul_f32_e32 v115, 0x3fb8aa3b, v115
	v_exp_f32_e32 v114, v114
	v_exp_f32_e32 v115, v115
	s_nop 0
	v_pk_fma_f32 v[4:5], v[4:5], v[114:115], v[50:51]
	s_cmp_le_u32 s0, 18
	s_cbranch_scc1 .Lc12_cmp_done
	v_mul_f32_e32 v116, 0x3fb8aa3b, v116
	v_mul_f32_e32 v117, 0x3fb8aa3b, v117
	v_exp_f32_e32 v116, v116
	v_exp_f32_e32 v117, v117
	s_nop 0
	v_pk_fma_f32 v[4:5], v[4:5], v[116:117], v[52:53]
	s_cmp_le_u32 s0, 19
	s_cbranch_scc1 .Lc12_cmp_done
	v_mul_f32_e32 v118, 0x3fb8aa3b, v118
	v_mul_f32_e32 v119, 0x3fb8aa3b, v119
	v_exp_f32_e32 v118, v118
	v_exp_f32_e32 v119, v119
	s_nop 0
	v_pk_fma_f32 v[4:5], v[4:5], v[118:119], v[54:55]
	s_cmp_le_u32 s0, 20
	s_cbranch_scc1 .Lc12_cmp_done
	v_mul_f32_e32 v120, 0x3fb8aa3b, v120
	v_mul_f32_e32 v121, 0x3fb8aa3b, v121
	v_exp_f32_e32 v120, v120
	v_exp_f32_e32 v121, v121
	s_nop 0
	v_pk_fma_f32 v[4:5], v[4:5], v[120:121], v[56:57]
	s_cmp_le_u32 s0, 21
	s_cbranch_scc1 .Lc12_cmp_done
	v_mul_f32_e32 v122, 0x3fb8aa3b, v122
	v_mul_f32_e32 v123, 0x3fb8aa3b, v123
	v_exp_f32_e32 v122, v122
	v_exp_f32_e32 v123, v123
	s_nop 0
	v_pk_fma_f32 v[4:5], v[4:5], v[122:123], v[58:59]
	s_cmp_le_u32 s0, 22
	s_cbranch_scc1 .Lc12_cmp_done
	v_mul_f32_e32 v124, 0x3fb8aa3b, v124
	v_mul_f32_e32 v125, 0x3fb8aa3b, v125
	v_exp_f32_e32 v124, v124
	v_exp_f32_e32 v125, v125
	s_nop 0
	v_pk_fma_f32 v[4:5], v[4:5], v[124:125], v[60:61]
	s_cmp_le_u32 s0, 23
	s_cbranch_scc1 .Lc12_cmp_done
	v_mul_f32_e32 v126, 0x3fb8aa3b, v126
	v_mul_f32_e32 v127, 0x3fb8aa3b, v127
	v_exp_f32_e32 v126, v126
	v_exp_f32_e32 v127, v127
	s_nop 0
	v_pk_fma_f32 v[4:5], v[4:5], v[126:127], v[62:63]
	s_cmp_le_u32 s0, 24
	s_cbranch_scc1 .Lc12_cmp_done
	v_mul_f32_e32 v128, 0x3fb8aa3b, v128
	v_mul_f32_e32 v129, 0x3fb8aa3b, v129
	v_exp_f32_e32 v128, v128
	v_exp_f32_e32 v129, v129
	s_nop 0
	v_pk_fma_f32 v[4:5], v[4:5], v[128:129], v[64:65]
	s_cmp_le_u32 s0, 25
	s_cbranch_scc1 .Lc12_cmp_done
	v_mul_f32_e32 v130, 0x3fb8aa3b, v130
	v_mul_f32_e32 v131, 0x3fb8aa3b, v131
	v_exp_f32_e32 v130, v130
	v_exp_f32_e32 v131, v131
	s_nop 0
	v_pk_fma_f32 v[4:5], v[4:5], v[130:131], v[66:67]
	s_cmp_le_u32 s0, 26
	s_cbranch_scc1 .Lc12_cmp_done
	v_mul_f32_e32 v132, 0x3fb8aa3b, v132
	v_mul_f32_e32 v133, 0x3fb8aa3b, v133
	v_exp_f32_e32 v132, v132
	v_exp_f32_e32 v133, v133
	s_nop 0
	v_pk_fma_f32 v[4:5], v[4:5], v[132:133], v[68:69]
	s_cmp_le_u32 s0, 27
	s_cbranch_scc1 .Lc12_cmp_done
	v_mul_f32_e32 v134, 0x3fb8aa3b, v134
	v_mul_f32_e32 v135, 0x3fb8aa3b, v135
	v_exp_f32_e32 v134, v134
	v_exp_f32_e32 v135, v135
	s_nop 0
	v_pk_fma_f32 v[4:5], v[4:5], v[134:135], v[70:71]
	s_cmp_le_u32 s0, 28
	s_cbranch_scc1 .Lc12_cmp_done
	v_mul_f32_e32 v136, 0x3fb8aa3b, v136
	v_mul_f32_e32 v137, 0x3fb8aa3b, v137
	v_exp_f32_e32 v136, v136
	v_exp_f32_e32 v137, v137
	s_nop 0
	v_pk_fma_f32 v[4:5], v[4:5], v[136:137], v[72:73]
	s_cmp_le_u32 s0, 29
	s_cbranch_scc1 .Lc12_cmp_done
	v_mul_f32_e32 v138, 0x3fb8aa3b, v138
	v_mul_f32_e32 v139, 0x3fb8aa3b, v139
	v_exp_f32_e32 v138, v138
	v_exp_f32_e32 v139, v139
	s_nop 0
	v_pk_fma_f32 v[4:5], v[4:5], v[138:139], v[74:75]
	s_cmp_le_u32 s0, 30
	s_cbranch_scc1 .Lc12_cmp_done
	v_mul_f32_e32 v140, 0x3fb8aa3b, v140
	v_mul_f32_e32 v141, 0x3fb8aa3b, v141
	v_exp_f32_e32 v140, v140
	v_exp_f32_e32 v141, v141
	s_nop 0
	v_pk_fma_f32 v[4:5], v[4:5], v[140:141], v[76:77]
	s_cmp_le_u32 s0, 31
	s_cbranch_scc1 .Lc12_cmp_done
	v_mul_f32_e32 v142, 0x3fb8aa3b, v142
	v_mul_f32_e32 v143, 0x3fb8aa3b, v143
	v_exp_f32_e32 v142, v142
	v_exp_f32_e32 v143, v143
	s_nop 0
	v_pk_fma_f32 v[4:5], v[4:5], v[142:143], v[78:79]
.Lc12_cmp_done:
	s_cmp_gt_u32 s0, 32
	s_cbranch_scc0 .Lc12_end
	s_sub_u32 s0, s0, 32
	s_branch .Lc12_batch
.Lc12_end:
.LBB0_1567:
	s_or_b64 exec, exec, s[38:39]
	v_lshlrev_b64 v[6:7], 17, v[6:7]
	v_lshl_or_b32 v6, v14, 2, v6
	v_lshl_add_u64 v[6:7], s[20:21], 0, v[6:7]
	s_mov_b32 s0, -16
